# cache-policy hint: nt on scan pass 2's last-use gate-branch loads so the streamed tensor does not displace the a/b tensors in the Infinity Cache
# speedup vs baseline: 1.0050x; 1.0050x over previous
.LBB0_1527:
	s_nop 0
	v_lshl_add_u64 v[12:13], s[0:1], 0, v[8:9]
	v_lshl_add_u64 v[14:15], s[0:1], 0, v[10:11]
	s_mov_b64 s[10:11], 0x2000
	v_lshl_add_u64 v[176:177], v[12:13], 0, s[8:9]
	v_lshl_add_u64 v[178:179], v[176:177], 0, s[10:11]
	v_lshl_add_u64 v[180:181], v[178:179], 0, s[10:11]
	v_lshl_add_u64 v[182:183], v[180:181], 0, s[10:11]
	global_load_dwordx4 v[80:83], v[176:177], off offset:-4096
	global_load_dwordx4 v[84:87], v[176:177], off offset:-4080
	global_load_dwordx4 v[96:99], v[176:177], off
	global_load_dwordx4 v[100:103], v[176:177], off offset:16
	global_load_dwordx4 v[112:115], v[178:179], off offset:-4096
	global_load_dwordx4 v[116:119], v[178:179], off offset:-4080
	global_load_dwordx4 v[128:131], v[178:179], off
	global_load_dwordx4 v[132:135], v[178:179], off offset:16
	global_load_dwordx4 v[144:147], v[180:181], off offset:-4096
	global_load_dwordx4 v[148:151], v[180:181], off offset:-4080
	global_load_dwordx4 v[160:163], v[180:181], off
	global_load_dwordx4 v[164:167], v[180:181], off offset:16
	global_load_dwordx4 v[32:35], v[182:183], off offset:-4096
	global_load_dwordx4 v[36:39], v[182:183], off offset:-4080
	global_load_dwordx4 v[60:63], v[182:183], off
	global_load_dwordx4 v[64:67], v[182:183], off offset:16
	s_mov_b64 s[10:11], 0x11000800
	v_lshl_add_u64 v[176:177], v[14:15], 0, s[10:11]
	s_mov_b64 s[10:11], 0x1800
	v_lshl_add_u64 v[178:179], v[176:177], 0, s[10:11]
	v_lshl_add_u64 v[180:181], v[178:179], 0, s[10:11]
	global_load_dwordx4 v[88:91], v[176:177], off offset:-2048
	global_load_dwordx4 v[104:107], v[176:177], off
	global_load_dwordx4 v[120:123], v[176:177], off offset:2048
	global_load_dwordx4 v[136:139], v[178:179], off offset:-2048
	global_load_dwordx4 v[152:155], v[178:179], off
	global_load_dwordx4 v[168:171], v[178:179], off offset:2048
	global_load_dwordx4 v[40:43], v[180:181], off offset:-2048
	global_load_dwordx4 v[68:71], v[180:181], off
	s_mov_b64 s[10:11], 0xd000800
	v_lshl_add_u64 v[176:177], v[14:15], 0, s[10:11]
	s_mov_b64 s[10:11], 0x1800
	v_lshl_add_u64 v[178:179], v[176:177], 0, s[10:11]
	v_lshl_add_u64 v[180:181], v[178:179], 0, s[10:11]
	global_load_dwordx4 v[92:95], v[176:177], off offset:-2048 nt
	global_load_dwordx4 v[108:111], v[176:177], off nt
	global_load_dwordx4 v[124:127], v[176:177], off offset:2048 nt
	global_load_dwordx4 v[140:143], v[178:179], off offset:-2048 nt
	global_load_dwordx4 v[156:159], v[178:179], off nt
	global_load_dwordx4 v[172:175], v[178:179], off offset:2048 nt
	global_load_dwordx4 v[44:47], v[180:181], off offset:-2048 nt
	global_load_dwordx4 v[72:75], v[180:181], off nt
	s_mov_b64 s[10:11], 0x09000800
	v_lshl_add_u64 v[76:77], v[14:15], 0, s[10:11]
	s_mov_b64 s[10:11], 0x1800
	v_lshl_add_u64 v[78:79], v[76:77], 0, s[10:11]
	v_lshl_add_u64 v[28:29], v[78:79], 0, s[10:11]
	v_lshl_add_u64 v[10:11], v[10:11], 0, s[46:47]
	v_lshl_add_u64 v[8:9], v[8:9], 0, s[64:65]
	s_waitcnt vmcnt(7)
	v_lshlrev_b32_e32 v56, 16, v88
	v_and_b32_e32 v57, 0xffff0000, v88
	v_pk_fma_f32 v[30:31], v[30:31], v[80:81], v[56:57]
	v_lshlrev_b32_e32 v58, 16, v92
	v_and_b32_e32 v59, 0xffff0000, v92
	v_pk_mul_f32 v[58:59], v[30:31], v[58:59]
	v_cvt_pk_bf16_f32 v12, v58, v59
	v_lshlrev_b32_e32 v56, 16, v89
	v_and_b32_e32 v57, 0xffff0000, v89
	v_pk_fma_f32 v[4:5], v[4:5], v[82:83], v[56:57]
	v_lshlrev_b32_e32 v58, 16, v93
	v_and_b32_e32 v59, 0xffff0000, v93
	v_pk_mul_f32 v[58:59], v[4:5], v[58:59]
	v_cvt_pk_bf16_f32 v13, v58, v59
	v_lshlrev_b32_e32 v56, 16, v90
	v_and_b32_e32 v57, 0xffff0000, v90
	v_pk_fma_f32 v[6:7], v[6:7], v[84:85], v[56:57]
	v_lshlrev_b32_e32 v58, 16, v94
	v_and_b32_e32 v59, 0xffff0000, v94
	v_pk_mul_f32 v[58:59], v[6:7], v[58:59]
	v_cvt_pk_bf16_f32 v14, v58, v59
	v_lshlrev_b32_e32 v56, 16, v91
	v_and_b32_e32 v57, 0xffff0000, v91
	v_pk_fma_f32 v[0:1], v[0:1], v[86:87], v[56:57]
	v_lshlrev_b32_e32 v58, 16, v95
	v_and_b32_e32 v59, 0xffff0000, v95
	v_pk_mul_f32 v[58:59], v[0:1], v[58:59]
	v_cvt_pk_bf16_f32 v15, v58, v59
	global_store_dwordx4 v[76:77], v[12:15], off offset:-2048
	s_waitcnt vmcnt(6)
	v_lshlrev_b32_e32 v56, 16, v104
	v_and_b32_e32 v57, 0xffff0000, v104
	v_pk_fma_f32 v[30:31], v[30:31], v[96:97], v[56:57]
	v_lshlrev_b32_e32 v58, 16, v108
	v_and_b32_e32 v59, 0xffff0000, v108
	v_pk_mul_f32 v[58:59], v[30:31], v[58:59]
	v_cvt_pk_bf16_f32 v52, v58, v59
	v_lshlrev_b32_e32 v56, 16, v105
	v_and_b32_e32 v57, 0xffff0000, v105
	v_pk_fma_f32 v[4:5], v[4:5], v[98:99], v[56:57]
	v_lshlrev_b32_e32 v58, 16, v109
	v_and_b32_e32 v59, 0xffff0000, v109
	v_pk_mul_f32 v[58:59], v[4:5], v[58:59]
	v_cvt_pk_bf16_f32 v53, v58, v59
	v_lshlrev_b32_e32 v56, 16, v106
	v_and_b32_e32 v57, 0xffff0000, v106
	v_pk_fma_f32 v[6:7], v[6:7], v[100:101], v[56:57]
	v_lshlrev_b32_e32 v58, 16, v110
	v_and_b32_e32 v59, 0xffff0000, v110
	v_pk_mul_f32 v[58:59], v[6:7], v[58:59]
	v_cvt_pk_bf16_f32 v54, v58, v59
	v_lshlrev_b32_e32 v56, 16, v107
	v_and_b32_e32 v57, 0xffff0000, v107
	v_pk_fma_f32 v[0:1], v[0:1], v[102:103], v[56:57]
	v_lshlrev_b32_e32 v58, 16, v111
	v_and_b32_e32 v59, 0xffff0000, v111
	v_pk_mul_f32 v[58:59], v[0:1], v[58:59]
	v_cvt_pk_bf16_f32 v55, v58, v59
	global_store_dwordx4 v[76:77], v[52:55], off
	s_waitcnt vmcnt(5)
	v_lshlrev_b32_e32 v56, 16, v120
	v_and_b32_e32 v57, 0xffff0000, v120
	v_pk_fma_f32 v[30:31], v[30:31], v[112:113], v[56:57]
	v_lshlrev_b32_e32 v58, 16, v124
	v_and_b32_e32 v59, 0xffff0000, v124
	v_pk_mul_f32 v[58:59], v[30:31], v[58:59]
	v_cvt_pk_bf16_f32 v12, v58, v59
	v_lshlrev_b32_e32 v56, 16, v121
	v_and_b32_e32 v57, 0xffff0000, v121
	v_pk_fma_f32 v[4:5], v[4:5], v[114:115], v[56:57]
	v_lshlrev_b32_e32 v58, 16, v125
	v_and_b32_e32 v59, 0xffff0000, v125
	v_pk_mul_f32 v[58:59], v[4:5], v[58:59]
	v_cvt_pk_bf16_f32 v13, v58, v59
	v_lshlrev_b32_e32 v56, 16, v122
	v_and_b32_e32 v57, 0xffff0000, v122
	v_pk_fma_f32 v[6:7], v[6:7], v[116:117], v[56:57]
	v_lshlrev_b32_e32 v58, 16, v126
	v_and_b32_e32 v59, 0xffff0000, v126
	v_pk_mul_f32 v[58:59], v[6:7], v[58:59]
	v_cvt_pk_bf16_f32 v14, v58, v59
	v_lshlrev_b32_e32 v56, 16, v123
	v_and_b32_e32 v57, 0xffff0000, v123
	v_pk_fma_f32 v[0:1], v[0:1], v[118:119], v[56:57]
	v_lshlrev_b32_e32 v58, 16, v127
	v_and_b32_e32 v59, 0xffff0000, v127
	v_pk_mul_f32 v[58:59], v[0:1], v[58:59]
	v_cvt_pk_bf16_f32 v15, v58, v59
	global_store_dwordx4 v[76:77], v[12:15], off offset:2048
	s_waitcnt vmcnt(4)
	v_lshlrev_b32_e32 v56, 16, v136
	v_and_b32_e32 v57, 0xffff0000, v136
	v_pk_fma_f32 v[30:31], v[30:31], v[128:129], v[56:57]
	v_lshlrev_b32_e32 v58, 16, v140
	v_and_b32_e32 v59, 0xffff0000, v140
	v_pk_mul_f32 v[58:59], v[30:31], v[58:59]
	v_cvt_pk_bf16_f32 v52, v58, v59
	v_lshlrev_b32_e32 v56, 16, v137
	v_and_b32_e32 v57, 0xffff0000, v137
	v_pk_fma_f32 v[4:5], v[4:5], v[130:131], v[56:57]
	v_lshlrev_b32_e32 v58, 16, v141
	v_and_b32_e32 v59, 0xffff0000, v141
	v_pk_mul_f32 v[58:59], v[4:5], v[58:59]
	v_cvt_pk_bf16_f32 v53, v58, v59
	v_lshlrev_b32_e32 v56, 16, v138
	v_and_b32_e32 v57, 0xffff0000, v138
	v_pk_fma_f32 v[6:7], v[6:7], v[132:133], v[56:57]
	v_lshlrev_b32_e32 v58, 16, v142
	v_and_b32_e32 v59, 0xffff0000, v142
	v_pk_mul_f32 v[58:59], v[6:7], v[58:59]
	v_cvt_pk_bf16_f32 v54, v58, v59
	v_lshlrev_b32_e32 v56, 16, v139
	v_and_b32_e32 v57, 0xffff0000, v139
	v_pk_fma_f32 v[0:1], v[0:1], v[134:135], v[56:57]
	v_lshlrev_b32_e32 v58, 16, v143
	v_and_b32_e32 v59, 0xffff0000, v143
	v_pk_mul_f32 v[58:59], v[0:1], v[58:59]
	v_cvt_pk_bf16_f32 v55, v58, v59
	global_store_dwordx4 v[78:79], v[52:55], off offset:-2048
	s_waitcnt vmcnt(3)
	v_lshlrev_b32_e32 v56, 16, v152
	v_and_b32_e32 v57, 0xffff0000, v152
	v_pk_fma_f32 v[30:31], v[30:31], v[144:145], v[56:57]
	v_lshlrev_b32_e32 v58, 16, v156
	v_and_b32_e32 v59, 0xffff0000, v156
	v_pk_mul_f32 v[58:59], v[30:31], v[58:59]
	v_cvt_pk_bf16_f32 v12, v58, v59
	v_lshlrev_b32_e32 v56, 16, v153
	v_and_b32_e32 v57, 0xffff0000, v153
	v_pk_fma_f32 v[4:5], v[4:5], v[146:147], v[56:57]
	v_lshlrev_b32_e32 v58, 16, v157
	v_and_b32_e32 v59, 0xffff0000, v157
	v_pk_mul_f32 v[58:59], v[4:5], v[58:59]
	v_cvt_pk_bf16_f32 v13, v58, v59
	v_lshlrev_b32_e32 v56, 16, v154
	v_and_b32_e32 v57, 0xffff0000, v154
	v_pk_fma_f32 v[6:7], v[6:7], v[148:149], v[56:57]
	v_lshlrev_b32_e32 v58, 16, v158
	v_and_b32_e32 v59, 0xffff0000, v158
	v_pk_mul_f32 v[58:59], v[6:7], v[58:59]
	v_cvt_pk_bf16_f32 v14, v58, v59
	v_lshlrev_b32_e32 v56, 16, v155
	v_and_b32_e32 v57, 0xffff0000, v155
	v_pk_fma_f32 v[0:1], v[0:1], v[150:151], v[56:57]
	v_lshlrev_b32_e32 v58, 16, v159
	v_and_b32_e32 v59, 0xffff0000, v159
	v_pk_mul_f32 v[58:59], v[0:1], v[58:59]
	v_cvt_pk_bf16_f32 v15, v58, v59
	global_store_dwordx4 v[78:79], v[12:15], off
	s_waitcnt vmcnt(2)
	v_lshlrev_b32_e32 v56, 16, v168
	v_and_b32_e32 v57, 0xffff0000, v168
	v_pk_fma_f32 v[30:31], v[30:31], v[160:161], v[56:57]
	v_lshlrev_b32_e32 v58, 16, v172
	v_and_b32_e32 v59, 0xffff0000, v172
	v_pk_mul_f32 v[58:59], v[30:31], v[58:59]
	v_cvt_pk_bf16_f32 v52, v58, v59
	v_lshlrev_b32_e32 v56, 16, v169
	v_and_b32_e32 v57, 0xffff0000, v169
	v_pk_fma_f32 v[4:5], v[4:5], v[162:163], v[56:57]
	v_lshlrev_b32_e32 v58, 16, v173
	v_and_b32_e32 v59, 0xffff0000, v173
	v_pk_mul_f32 v[58:59], v[4:5], v[58:59]
	v_cvt_pk_bf16_f32 v53, v58, v59
	v_lshlrev_b32_e32 v56, 16, v170
	v_and_b32_e32 v57, 0xffff0000, v170
	v_pk_fma_f32 v[6:7], v[6:7], v[164:165], v[56:57]
	v_lshlrev_b32_e32 v58, 16, v174
	v_and_b32_e32 v59, 0xffff0000, v174
	v_pk_mul_f32 v[58:59], v[6:7], v[58:59]
	v_cvt_pk_bf16_f32 v54, v58, v59
	v_lshlrev_b32_e32 v56, 16, v171
	v_and_b32_e32 v57, 0xffff0000, v171
	v_pk_fma_f32 v[0:1], v[0:1], v[166:167], v[56:57]
	v_lshlrev_b32_e32 v58, 16, v175
	v_and_b32_e32 v59, 0xffff0000, v175
	v_pk_mul_f32 v[58:59], v[0:1], v[58:59]
	v_cvt_pk_bf16_f32 v55, v58, v59
	global_store_dwordx4 v[78:79], v[52:55], off offset:2048
	s_waitcnt vmcnt(1)
	v_lshlrev_b32_e32 v56, 16, v40
	v_and_b32_e32 v57, 0xffff0000, v40
	v_pk_fma_f32 v[30:31], v[30:31], v[32:33], v[56:57]
	v_lshlrev_b32_e32 v58, 16, v44
	v_and_b32_e32 v59, 0xffff0000, v44
	v_pk_mul_f32 v[58:59], v[30:31], v[58:59]
	v_cvt_pk_bf16_f32 v12, v58, v59
	v_lshlrev_b32_e32 v56, 16, v41
	v_and_b32_e32 v57, 0xffff0000, v41
	v_pk_fma_f32 v[4:5], v[4:5], v[34:35], v[56:57]
	v_lshlrev_b32_e32 v58, 16, v45
	v_and_b32_e32 v59, 0xffff0000, v45
	v_pk_mul_f32 v[58:59], v[4:5], v[58:59]
	v_cvt_pk_bf16_f32 v13, v58, v59
	v_lshlrev_b32_e32 v56, 16, v42
	v_and_b32_e32 v57, 0xffff0000, v42
	v_pk_fma_f32 v[6:7], v[6:7], v[36:37], v[56:57]
	v_lshlrev_b32_e32 v58, 16, v46
	v_and_b32_e32 v59, 0xffff0000, v46
	v_pk_mul_f32 v[58:59], v[6:7], v[58:59]
	v_cvt_pk_bf16_f32 v14, v58, v59
	v_lshlrev_b32_e32 v56, 16, v43
	v_and_b32_e32 v57, 0xffff0000, v43
	v_pk_fma_f32 v[0:1], v[0:1], v[38:39], v[56:57]
	v_lshlrev_b32_e32 v58, 16, v47
	v_and_b32_e32 v59, 0xffff0000, v47
	v_pk_mul_f32 v[58:59], v[0:1], v[58:59]
	v_cvt_pk_bf16_f32 v15, v58, v59
	global_store_dwordx4 v[28:29], v[12:15], off offset:-2048
	s_waitcnt vmcnt(0)
	v_lshlrev_b32_e32 v56, 16, v68
	v_and_b32_e32 v57, 0xffff0000, v68
	v_pk_fma_f32 v[30:31], v[30:31], v[60:61], v[56:57]
	v_lshlrev_b32_e32 v58, 16, v72
	v_and_b32_e32 v59, 0xffff0000, v72
	v_pk_mul_f32 v[58:59], v[30:31], v[58:59]
	v_cvt_pk_bf16_f32 v52, v58, v59
	v_lshlrev_b32_e32 v56, 16, v69
	v_and_b32_e32 v57, 0xffff0000, v69
	v_pk_fma_f32 v[4:5], v[4:5], v[62:63], v[56:57]
	v_lshlrev_b32_e32 v58, 16, v73
	v_and_b32_e32 v59, 0xffff0000, v73
	v_pk_mul_f32 v[58:59], v[4:5], v[58:59]
	v_cvt_pk_bf16_f32 v53, v58, v59
	v_lshlrev_b32_e32 v56, 16, v70
	v_and_b32_e32 v57, 0xffff0000, v70
	v_pk_fma_f32 v[6:7], v[6:7], v[64:65], v[56:57]
	v_lshlrev_b32_e32 v58, 16, v74
	v_and_b32_e32 v59, 0xffff0000, v74
	v_pk_mul_f32 v[58:59], v[6:7], v[58:59]
	v_cvt_pk_bf16_f32 v54, v58, v59
	v_lshlrev_b32_e32 v56, 16, v71
	v_and_b32_e32 v57, 0xffff0000, v71
	v_pk_fma_f32 v[0:1], v[0:1], v[66:67], v[56:57]
	v_lshlrev_b32_e32 v58, 16, v75
	v_and_b32_e32 v59, 0xffff0000, v75
	v_pk_mul_f32 v[58:59], v[0:1], v[58:59]
	v_cvt_pk_bf16_f32 v55, v58, v59
	global_store_dwordx4 v[28:29], v[52:55], off
	s_add_i32 s2, s2, -8
	s_cmp_eq_u32 s2, 0
	s_cbranch_scc0 .LBB0_1527
	v_readlane_b32 s2, v254, 0
	v_readlane_b32 s3, v254, 1
	s_add_i32 s16, s16, s2
	v_readlane_b32 s2, v255, 28
	v_readlane_b32 s3, v255, 29
	s_cmpk_gt_i32 s16, 0xff
	s_nop 0
	v_lshl_add_u64 v[22:23], v[22:23], 0, s[2:3]
	v_readlane_b32 s2, v254, 13
	v_readlane_b32 s3, v254, 14
	s_nop 1
	v_lshl_add_u64 v[24:25], v[24:25], 0, s[2:3]
	v_readlane_b32 s2, v254, 11
	v_readlane_b32 s3, v254, 12
	s_nop 1
	v_lshl_add_u64 v[26:27], v[26:27], 0, s[2:3]
	s_cbranch_scc0 .LBB0_1512
